# S5 pass C split: RWKV workgroups run their second wave item after the (now shorter, fused-reduction) RWKV scan in phase 4; phase 3 keeps one item per wave there; normaliser scan on workgroups 192/208
# speedup vs baseline: 1.0178x; 1.0178x over previous
.LBB0_817:
	s_cmp_eq_u32 s53, 3
	s_cbranch_scc1 .Ls5_go
	s_cmp_lg_u32 s53, 4
	s_cbranch_scc1 .LBB0_885
	s_cmpk_gt_u32 s73, 0xdf
	s_cbranch_scc1 .LBB0_885
.Ls5_go:
	s_mov_b32 s2, s73
	v_mov_b32_e32 v45, v226
	v_mov_b32_e32 v44, v226
	s_mov_b32 s4, s54
	s_cmp_lg_u32 s53, 3
	s_cbranch_scc1 .LBB0_857
	s_andn2_b32 s4, s2, 16
	s_cmp_lg_u32 s4, 0xc0
	s_cbranch_scc1 .LBB0_857
	s_load_dwordx2 s[4:5], s[0:1], 0x150
	s_load_dwordx2 s[6:7], s[0:1], 0x150
	s_load_dwordx2 s[8:9], s[0:1], 0x150
	s_load_dwordx2 s[10:11], s[0:1], 0x150
	s_load_dwordx2 s[12:13], s[0:1], 0x150
	v_mov_b32_e32 v46, v226
	s_lshl_b32 s19, s2, 5
	s_and_b32 s19, s19, 0x200
	s_nop 0
	v_add_u32_e32 v46, s19, v46
	s_movk_i32 s19, 0x400
	s_nop 0
	v_cmp_gt_i32_e32 vcc, s19, v46
	s_and_saveexec_b64 s[22:23], vcc
	s_cbranch_execz .LBB0_856
	v_mov_b32_e32 v0, 2
	v_cmp_eq_u32_sdwa s[24:25], v46, v169 src0_sel:BYTE_0 src1_sel:DWORD
	v_lshlrev_b32_sdwa v168, v0, v46 dst_sel:DWORD dst_unused:UNUSED_PAD src0_sel:DWORD src1_sel:BYTE_0
	s_mov_b64 s[26:27], 0
	s_branch .LBB0_822

.LBB0_857:
	v_ashrrev_i32_e32 v0, 6, v45
	v_lshl_add_u32 v33, s2, 3, v0
	s_waitcnt lgkmcnt(0)
	s_mov_b32 s4, s54
	s_movk_i32 s99, 0x1000
	s_cmp_eq_u32 s53, 4
	s_cbranch_scc0 .Ls5_p3
	v_add_u32_e32 v33, 0x800, v33
	s_branch .Ls5_lim
.Ls5_p3:
	s_cmpk_gt_u32 s73, 0xdf
	s_cbranch_scc1 .Ls5_lim
	s_movk_i32 s99, 0x800
.Ls5_lim:
	v_cmp_gt_i32_e32 vcc, s99, v33
	s_and_saveexec_b64 s[12:13], vcc
	s_cbranch_execz .LBB0_884
	v_bfe_u32 v11, v44, 2, 4
	v_and_b32_e32 v13, 12, v11
	v_or_b32_e32 v17, 1, v13
	v_lshlrev_b32_e32 v18, 6, v17
	v_lshlrev_b32_e32 v94, 9, v17
	v_or_b32_e32 v17, 2, v13
	v_lshlrev_b32_e32 v19, 6, v17
	v_lshlrev_b32_e32 v95, 9, v17
	v_or_b32_e32 v17, 3, v11
	v_lshlrev_b32_e32 v20, 6, v17
	v_lshlrev_b32_e32 v96, 9, v17
	v_or_b32_e32 v17, 16, v13
	v_lshlrev_b32_e32 v21, 6, v17
	v_lshlrev_b32_e32 v97, 9, v17
	v_or_b32_e32 v17, 17, v13
	v_lshlrev_b32_e32 v22, 6, v17
	v_lshlrev_b32_e32 v98, 9, v17
	v_or_b32_e32 v17, 18, v13
	v_lshlrev_b32_e32 v23, 6, v17
	v_lshlrev_b32_e32 v99, 9, v17
	v_or_b32_e32 v17, 19, v11
	v_lshlrev_b32_e32 v24, 6, v17
	v_lshlrev_b32_e32 v100, 9, v17
	v_or_b32_e32 v17, 32, v13
	v_lshlrev_b32_e32 v25, 6, v17
	v_lshlrev_b32_e32 v101, 9, v17
	v_or_b32_e32 v17, 33, v13
	v_lshlrev_b32_e32 v26, 6, v17
	v_lshlrev_b32_e32 v102, 9, v17
	v_or_b32_e32 v17, 34, v13
	s_movk_i32 s2, 0x2200
	v_lshlrev_b32_e32 v27, 6, v17
	v_lshlrev_b32_e32 v103, 9, v17
	v_or_b32_e32 v17, 35, v11
	v_mul_lo_u32 v1, v0, s2
	v_lshlrev_b32_e32 v3, 12, v0
	v_readlane_b32 s2, v255, 9
	v_bfe_u32 v9, v44, 1, 5
	v_lshlrev_b32_e32 v28, 6, v17
	v_lshlrev_b32_e32 v104, 9, v17
	v_or_b32_e32 v17, 48, v13
	v_and_b32_e32 v35, 63, v44
	v_add_u32_e32 v1, 0, v1
	v_add_u32_e32 v5, s2, v3
	v_and_b32_e32 v2, 15, v44
	v_and_b32_e32 v4, 24, v9
	v_lshlrev_b32_e32 v16, 6, v13
	v_lshlrev_b32_e32 v93, 9, v13
	v_lshlrev_b32_e32 v29, 6, v17
	v_lshlrev_b32_e32 v105, 9, v17
	v_or_b32_e32 v17, 49, v13
	v_or_b32_e32 v13, 50, v13
	v_or_b32_e32 v11, 51, v11
	s_lshl_b32 s19, s4, 3
	v_mul_u32_u24_e32 v0, 0x1a00, v35
	v_lshlrev_b32_e32 v7, 6, v35
	v_or_b32_e32 v6, 7, v9
	v_or_b32_e32 v8, 39, v9
	v_or_b32_e32 v10, 0x47, v9
	v_or_b32_e32 v12, 0x67, v9
	v_readlane_b32 s4, v255, 27
	v_lshl_add_u32 v9, v4, 1, v1
	v_lshl_add_u32 v14, v2, 2, v5
	v_mul_u32_u24_e32 v15, 0x110, v2
	v_lshlrev_b32_e32 v30, 6, v17
	v_lshlrev_b32_e32 v106, 9, v17
	v_lshlrev_b32_e32 v17, 6, v13
	v_lshlrev_b32_e32 v107, 9, v13
	v_lshlrev_b32_e32 v13, 6, v11
	v_lshlrev_b32_e32 v32, 4, v35
	v_lshlrev_b32_e32 v34, 6, v2
	v_or_b32_e32 v92, s4, v2
	v_lshlrev_b32_e32 v108, 9, v11
	v_lshl_add_u32 v109, v35, 1, v1
	v_lshlrev_b32_e32 v36, 3, v35
	v_mov_b32_e32 v37, v169
	v_add_u32_e32 v110, 0, v3
	s_mov_b64 s[22:23], 0
	v_lshlrev_b32_e32 v38, 2, v0
	v_add_u32_e32 v111, v5, v7
	v_lshlrev_b32_e32 v40, 2, v4
	v_lshlrev_b32_e32 v42, 2, v6
	v_lshlrev_b32_e32 v44, 2, v8
	v_lshlrev_b32_e32 v46, 2, v10
	v_lshlrev_b32_e32 v48, 2, v12
	v_lshlrev_b32_e32 v50, 1, v2
	v_add_u32_e32 v112, v14, v16
	v_add_u32_e32 v113, v14, v18
	v_add_u32_e32 v114, v14, v19
	v_add_u32_e32 v115, v14, v20
	v_add_u32_e32 v116, v14, v21
	v_add_u32_e32 v117, v14, v22
	v_add_u32_e32 v118, v14, v23
	v_add_u32_e32 v119, v14, v24
	v_add_u32_e32 v120, v14, v25
	v_add_u32_e32 v121, v14, v26
	v_add_u32_e32 v122, v14, v27
	v_add_u32_e32 v123, v14, v28
	v_add_u32_e32 v124, v14, v29
	v_add_u32_e32 v125, v14, v30
	v_add_u32_e32 v126, v14, v17
	v_add_u32_e32 v127, v14, v13
	v_add_u32_e32 v128, v9, v15
	v_readlane_b32 s5, v255, 28

.LBB0_882:
	ds_read_b128 v[130:133], v252 offset:2048
	ds_read_b128 v[134:137], v252 offset:2064
	v_sub_f32_e32 v139, 0, v52
	s_waitcnt lgkmcnt(0)
	s_nop 1
	v_mfma_f32_32x32x2_f32 v[176:191], v130, v54, 0
	v_mfma_f32_32x32x2_f32 v[192:207], v130, v72, 0
	v_mfma_f32_32x32x2_f32 v[208:223], v130, v55, 0
	v_mfma_f32_32x32x2_f32 v[144:159], v130, v73, 0
	v_mfma_f32_32x32x2_f32 v[176:191], v131, v56, v[176:191]
	v_mfma_f32_32x32x2_f32 v[192:207], v131, v74, v[192:207]
	v_mfma_f32_32x32x2_f32 v[208:223], v131, v57, v[208:223]
	v_mfma_f32_32x32x2_f32 v[144:159], v131, v75, v[144:159]
	v_mfma_f32_32x32x2_f32 v[176:191], v132, v58, v[176:191]
	v_mfma_f32_32x32x2_f32 v[192:207], v132, v76, v[192:207]
	v_mfma_f32_32x32x2_f32 v[208:223], v132, v59, v[208:223]
	v_mfma_f32_32x32x2_f32 v[144:159], v132, v77, v[144:159]
	v_mfma_f32_32x32x2_f32 v[176:191], v133, v60, v[176:191]
	v_mfma_f32_32x32x2_f32 v[192:207], v133, v78, v[192:207]
	v_mfma_f32_32x32x2_f32 v[208:223], v133, v61, v[208:223]
	v_mfma_f32_32x32x2_f32 v[144:159], v133, v79, v[144:159]
	v_mfma_f32_32x32x2_f32 v[176:191], v134, v62, v[176:191]
	v_mfma_f32_32x32x2_f32 v[192:207], v134, v80, v[192:207]
	v_mfma_f32_32x32x2_f32 v[208:223], v134, v63, v[208:223]
	v_mfma_f32_32x32x2_f32 v[144:159], v134, v81, v[144:159]
	v_mfma_f32_32x32x2_f32 v[176:191], v135, v64, v[176:191]
	v_mfma_f32_32x32x2_f32 v[192:207], v135, v82, v[192:207]
	v_mfma_f32_32x32x2_f32 v[208:223], v135, v65, v[208:223]
	v_mfma_f32_32x32x2_f32 v[144:159], v135, v83, v[144:159]
	v_mfma_f32_32x32x2_f32 v[176:191], v136, v68, v[176:191]
	v_mfma_f32_32x32x2_f32 v[192:207], v136, v84, v[192:207]
	v_mfma_f32_32x32x2_f32 v[208:223], v136, v69, v[208:223]
	v_mfma_f32_32x32x2_f32 v[144:159], v136, v85, v[144:159]
	v_mfma_f32_32x32x2_f32 v[176:191], v137, v70, v[176:191]
	v_mfma_f32_32x32x2_f32 v[192:207], v137, v86, v[192:207]
	v_mfma_f32_32x32x2_f32 v[208:223], v137, v71, v[208:223]
	v_mfma_f32_32x32x2_f32 v[144:159], v137, v87, v[144:159]
	s_nop 7
	s_nop 7
	s_nop 3
	v_permlane32_swap_b32_e32 v176, v192
	v_permlane32_swap_b32_e32 v208, v144
	v_permlane32_swap_b32_e32 v177, v193
	v_permlane32_swap_b32_e32 v209, v145
	v_permlane32_swap_b32_e32 v178, v194
	v_permlane32_swap_b32_e32 v210, v146
	v_permlane32_swap_b32_e32 v179, v195
	v_permlane32_swap_b32_e32 v211, v147
	v_permlane32_swap_b32_e32 v180, v196
	v_permlane32_swap_b32_e32 v212, v148
	v_permlane32_swap_b32_e32 v181, v197
	v_permlane32_swap_b32_e32 v213, v149
	v_permlane32_swap_b32_e32 v182, v198
	v_permlane32_swap_b32_e32 v214, v150
	v_permlane32_swap_b32_e32 v183, v199
	v_permlane32_swap_b32_e32 v215, v151
	v_permlane32_swap_b32_e32 v184, v200
	v_permlane32_swap_b32_e32 v216, v152
	v_permlane32_swap_b32_e32 v185, v201
	v_permlane32_swap_b32_e32 v217, v153
	v_permlane32_swap_b32_e32 v186, v202
	v_permlane32_swap_b32_e32 v218, v154
	v_permlane32_swap_b32_e32 v187, v203
	v_permlane32_swap_b32_e32 v219, v155
	v_permlane32_swap_b32_e32 v188, v204
	v_permlane32_swap_b32_e32 v220, v156
	v_permlane32_swap_b32_e32 v189, v205
	v_permlane32_swap_b32_e32 v221, v157
	v_permlane32_swap_b32_e32 v190, v206
	v_permlane32_swap_b32_e32 v222, v158
	v_permlane32_swap_b32_e32 v191, v207
	v_permlane32_swap_b32_e32 v223, v159
	s_nop 1
	v_fmac_f32_e32 v176, v88, v66
	v_fmac_f32_e32 v208, v88, v67
	v_fmac_f32_e32 v176, v52, v67
	v_fmac_f32_e32 v208, v139, v66
	v_cvt_pk_bf16_f32 v140, v176, v208
	ds_write_b16_d16_hi v109, v140
	ds_write_b16 v109, v140 offset:128
	v_fmac_f32_e32 v177, v88, v176
	v_fmac_f32_e32 v209, v88, v208
	v_fmac_f32_e32 v177, v52, v208
	v_fmac_f32_e32 v209, v139, v176
	v_cvt_pk_bf16_f32 v141, v177, v209
	ds_write_b16_d16_hi v109, v141 offset:272
	ds_write_b16 v109, v141 offset:400
	v_fmac_f32_e32 v178, v88, v177
	v_fmac_f32_e32 v210, v88, v209
	v_fmac_f32_e32 v178, v52, v209
	v_fmac_f32_e32 v210, v139, v177
	v_cvt_pk_bf16_f32 v140, v178, v210
	ds_write_b16_d16_hi v109, v140 offset:544
	ds_write_b16 v109, v140 offset:672
	v_fmac_f32_e32 v179, v88, v178
	v_fmac_f32_e32 v211, v88, v210
	v_fmac_f32_e32 v179, v52, v210
	v_fmac_f32_e32 v211, v139, v178
	v_cvt_pk_bf16_f32 v141, v179, v211
	ds_write_b16_d16_hi v109, v141 offset:816
	ds_write_b16 v109, v141 offset:944
	s_waitcnt lgkmcnt(4)
	v_fmac_f32_e32 v192, v88, v179
	v_fmac_f32_e32 v144, v88, v211
	v_fmac_f32_e32 v192, v52, v211
	v_fmac_f32_e32 v144, v139, v179
	v_cvt_pk_bf16_f32 v140, v192, v144
	ds_write_b16_d16_hi v109, v140 offset:1088
	ds_write_b16 v109, v140 offset:1216
	v_fmac_f32_e32 v193, v88, v192
	v_fmac_f32_e32 v145, v88, v144
	v_fmac_f32_e32 v193, v52, v144
	v_fmac_f32_e32 v145, v139, v192
	v_cvt_pk_bf16_f32 v141, v193, v145
	ds_write_b16_d16_hi v109, v141 offset:1360
	ds_write_b16 v109, v141 offset:1488
	v_fmac_f32_e32 v194, v88, v193
	v_fmac_f32_e32 v146, v88, v145
	v_fmac_f32_e32 v194, v52, v145
	v_fmac_f32_e32 v146, v139, v193
	v_cvt_pk_bf16_f32 v140, v194, v146
	ds_write_b16_d16_hi v109, v140 offset:1632
	ds_write_b16 v109, v140 offset:1760
	v_fmac_f32_e32 v195, v88, v194
	v_fmac_f32_e32 v147, v88, v146
	v_fmac_f32_e32 v195, v52, v146
	v_fmac_f32_e32 v147, v139, v194
	v_cvt_pk_bf16_f32 v141, v195, v147
	ds_write_b16_d16_hi v109, v141 offset:1904
	ds_write_b16 v109, v141 offset:2032
	s_waitcnt lgkmcnt(4)
	v_fmac_f32_e32 v180, v88, v195
	v_fmac_f32_e32 v212, v88, v147
	v_fmac_f32_e32 v180, v52, v147
	v_fmac_f32_e32 v212, v139, v195
	v_cvt_pk_bf16_f32 v140, v180, v212
	ds_write_b16_d16_hi v109, v140 offset:2176
	ds_write_b16 v109, v140 offset:2304
	v_fmac_f32_e32 v181, v88, v180
	v_fmac_f32_e32 v213, v88, v212
	v_fmac_f32_e32 v181, v52, v212
	v_fmac_f32_e32 v213, v139, v180
	v_cvt_pk_bf16_f32 v141, v181, v213
	ds_write_b16_d16_hi v109, v141 offset:2448
	ds_write_b16 v109, v141 offset:2576
	v_fmac_f32_e32 v182, v88, v181
	v_fmac_f32_e32 v214, v88, v213
	v_fmac_f32_e32 v182, v52, v213
	v_fmac_f32_e32 v214, v139, v181
	v_cvt_pk_bf16_f32 v140, v182, v214
	ds_write_b16_d16_hi v109, v140 offset:2720
	ds_write_b16 v109, v140 offset:2848
	v_fmac_f32_e32 v183, v88, v182
	v_fmac_f32_e32 v215, v88, v214
	v_fmac_f32_e32 v183, v52, v214
	v_fmac_f32_e32 v215, v139, v182
	v_cvt_pk_bf16_f32 v141, v183, v215
	ds_write_b16_d16_hi v109, v141 offset:2992
	ds_write_b16 v109, v141 offset:3120
	s_waitcnt lgkmcnt(4)
	v_fmac_f32_e32 v196, v88, v183
	v_fmac_f32_e32 v148, v88, v215
	v_fmac_f32_e32 v196, v52, v215
	v_fmac_f32_e32 v148, v139, v183
	v_cvt_pk_bf16_f32 v140, v196, v148
	ds_write_b16_d16_hi v109, v140 offset:3264
	ds_write_b16 v109, v140 offset:3392
	v_fmac_f32_e32 v197, v88, v196
	v_fmac_f32_e32 v149, v88, v148
	v_fmac_f32_e32 v197, v52, v148
	v_fmac_f32_e32 v149, v139, v196
	v_cvt_pk_bf16_f32 v141, v197, v149
	ds_write_b16_d16_hi v109, v141 offset:3536
	ds_write_b16 v109, v141 offset:3664
	v_fmac_f32_e32 v198, v88, v197
	v_fmac_f32_e32 v150, v88, v149
	v_fmac_f32_e32 v198, v52, v149
	v_fmac_f32_e32 v150, v139, v197
	v_cvt_pk_bf16_f32 v140, v198, v150
	ds_write_b16_d16_hi v109, v140 offset:3808
	ds_write_b16 v109, v140 offset:3936
	v_fmac_f32_e32 v199, v88, v198
	v_fmac_f32_e32 v151, v88, v150
	v_fmac_f32_e32 v199, v52, v150
	v_fmac_f32_e32 v151, v139, v198
	v_cvt_pk_bf16_f32 v141, v199, v151
	ds_write_b16_d16_hi v109, v141 offset:4080
	ds_write_b16 v109, v141 offset:4208
	s_waitcnt lgkmcnt(4)
	v_fmac_f32_e32 v184, v88, v199
	v_fmac_f32_e32 v216, v88, v151
	v_fmac_f32_e32 v184, v52, v151
	v_fmac_f32_e32 v216, v139, v199
	v_cvt_pk_bf16_f32 v140, v184, v216
	ds_write_b16_d16_hi v109, v140 offset:4352
	ds_write_b16 v109, v140 offset:4480
	v_fmac_f32_e32 v185, v88, v184
	v_fmac_f32_e32 v217, v88, v216
	v_fmac_f32_e32 v185, v52, v216
	v_fmac_f32_e32 v217, v139, v184
	v_cvt_pk_bf16_f32 v141, v185, v217
	ds_write_b16_d16_hi v109, v141 offset:4624
	ds_write_b16 v109, v141 offset:4752
	v_fmac_f32_e32 v186, v88, v185
	v_fmac_f32_e32 v218, v88, v217
	v_fmac_f32_e32 v186, v52, v217
	v_fmac_f32_e32 v218, v139, v185
	v_cvt_pk_bf16_f32 v140, v186, v218
	ds_write_b16_d16_hi v109, v140 offset:4896
	ds_write_b16 v109, v140 offset:5024
	v_fmac_f32_e32 v187, v88, v186
	v_fmac_f32_e32 v219, v88, v218
	v_fmac_f32_e32 v187, v52, v218
	v_fmac_f32_e32 v219, v139, v186
	v_cvt_pk_bf16_f32 v141, v187, v219
	ds_write_b16_d16_hi v109, v141 offset:5168
	ds_write_b16 v109, v141 offset:5296
	s_waitcnt lgkmcnt(4)
	v_fmac_f32_e32 v200, v88, v187
	v_fmac_f32_e32 v152, v88, v219
	v_fmac_f32_e32 v200, v52, v219
	v_fmac_f32_e32 v152, v139, v187
	v_cvt_pk_bf16_f32 v140, v200, v152
	ds_write_b16_d16_hi v109, v140 offset:5440
	ds_write_b16 v109, v140 offset:5568
	v_fmac_f32_e32 v201, v88, v200
	v_fmac_f32_e32 v153, v88, v152
	v_fmac_f32_e32 v201, v52, v152
	v_fmac_f32_e32 v153, v139, v200
	v_cvt_pk_bf16_f32 v141, v201, v153
	ds_write_b16_d16_hi v109, v141 offset:5712
	ds_write_b16 v109, v141 offset:5840
	v_fmac_f32_e32 v202, v88, v201
	v_fmac_f32_e32 v154, v88, v153
	v_fmac_f32_e32 v202, v52, v153
	v_fmac_f32_e32 v154, v139, v201
	v_cvt_pk_bf16_f32 v140, v202, v154
	ds_write_b16_d16_hi v109, v140 offset:5984
	ds_write_b16 v109, v140 offset:6112
	v_fmac_f32_e32 v203, v88, v202
	v_fmac_f32_e32 v155, v88, v154
	v_fmac_f32_e32 v203, v52, v154
	v_fmac_f32_e32 v155, v139, v202
	v_cvt_pk_bf16_f32 v141, v203, v155
	ds_write_b16_d16_hi v109, v141 offset:6256
	ds_write_b16 v109, v141 offset:6384
	s_waitcnt lgkmcnt(4)
	v_fmac_f32_e32 v188, v88, v203
	v_fmac_f32_e32 v220, v88, v155
	v_fmac_f32_e32 v188, v52, v155
	v_fmac_f32_e32 v220, v139, v203
	v_cvt_pk_bf16_f32 v140, v188, v220
	ds_write_b16_d16_hi v109, v140 offset:6528
	ds_write_b16 v109, v140 offset:6656
	v_fmac_f32_e32 v189, v88, v188
	v_fmac_f32_e32 v221, v88, v220
	v_fmac_f32_e32 v189, v52, v220
	v_fmac_f32_e32 v221, v139, v188
	v_cvt_pk_bf16_f32 v141, v189, v221
	ds_write_b16_d16_hi v109, v141 offset:6800
	ds_write_b16 v109, v141 offset:6928
	v_fmac_f32_e32 v190, v88, v189
	v_fmac_f32_e32 v222, v88, v221
	v_fmac_f32_e32 v190, v52, v221
	v_fmac_f32_e32 v222, v139, v189
	v_cvt_pk_bf16_f32 v140, v190, v222
	ds_write_b16_d16_hi v109, v140 offset:7072
	ds_write_b16 v109, v140 offset:7200
	v_fmac_f32_e32 v191, v88, v190
	v_fmac_f32_e32 v223, v88, v222
	v_fmac_f32_e32 v191, v52, v222
	v_fmac_f32_e32 v223, v139, v190
	v_cvt_pk_bf16_f32 v141, v191, v223
	ds_write_b16_d16_hi v109, v141 offset:7344
	ds_write_b16 v109, v141 offset:7472
	s_waitcnt lgkmcnt(4)
	v_fmac_f32_e32 v204, v88, v191
	v_fmac_f32_e32 v156, v88, v223
	v_fmac_f32_e32 v204, v52, v223
	v_fmac_f32_e32 v156, v139, v191
	v_cvt_pk_bf16_f32 v140, v204, v156
	ds_write_b16_d16_hi v109, v140 offset:7616
	ds_write_b16 v109, v140 offset:7744
	v_fmac_f32_e32 v205, v88, v204
	v_fmac_f32_e32 v157, v88, v156
	v_fmac_f32_e32 v205, v52, v156
	v_fmac_f32_e32 v157, v139, v204
	v_cvt_pk_bf16_f32 v141, v205, v157
	ds_write_b16_d16_hi v109, v141 offset:7888
	ds_write_b16 v109, v141 offset:8016
	v_fmac_f32_e32 v206, v88, v205
	v_fmac_f32_e32 v158, v88, v157
	v_fmac_f32_e32 v206, v52, v157
	v_fmac_f32_e32 v158, v139, v205
	v_cvt_pk_bf16_f32 v140, v206, v158
	ds_write_b16_d16_hi v109, v140 offset:8160
	ds_write_b16 v109, v140 offset:8288
	v_fmac_f32_e32 v207, v88, v206
	v_fmac_f32_e32 v159, v88, v158
	v_fmac_f32_e32 v207, v52, v158
	v_fmac_f32_e32 v159, v139, v206
	v_cvt_pk_bf16_f32 v141, v207, v159
	ds_write_b16_d16_hi v109, v141 offset:8432
	ds_write_b16 v109, v141 offset:8560
	s_waitcnt lgkmcnt(4)
	v_mov_b32_e32 v66, v207
	v_mov_b32_e32 v67, v159
	s_waitcnt lgkmcnt(0)
	ds_read_b128 v[16:19], v128
	ds_read_b128 v[24:27], v128 offset:64
	v_add_u32_e32 v33, s19, v33
	s_movk_i32 s2, 0xfff
	v_cmp_le_i32_e32 vcc, s99, v33
	s_or_b64 s[22:23], vcc, s[22:23]
	s_waitcnt lgkmcnt(1)
	v_mfma_f32_16x16x32_bf16 v[16:19], v[16:19], v[0:3], 0
	s_waitcnt lgkmcnt(0)
	v_mfma_f32_16x16x32_bf16 v[16:19], v[24:27], v[4:7], v[16:19]
	ds_read_b128 v[24:27], v128 offset:128
	s_waitcnt lgkmcnt(0)
	v_mfma_f32_16x16x32_bf16 v[16:19], v[24:27], v[8:11], v[16:19]
	ds_read_b128 v[24:27], v128 offset:192
	s_waitcnt lgkmcnt(0)
	v_mfma_f32_16x16x32_bf16 v[16:19], v[24:27], v[12:15], v[16:19]
	ds_read_b32 v24, v120
	s_waitcnt lgkmcnt(0)
	s_nop 5
	v_fma_f32 v16, v23, v24, v16
	v_mul_f32_e32 v24, 0x3d372713, v16
	v_mul_f32_e32 v24, v16, v24
	v_fma_f32 v24, v16, v24, v16
	v_mul_f32_e32 v24, 0x3f4c422a, v24
	v_add_f32_e32 v24, v24, v24
	v_mul_f32_e32 v24, 0x3fb8aa3b, v24
	v_exp_f32_e32 v24, v24
	v_mul_f32_e32 v16, 0.5, v16
	v_add_f32_e32 v24, 1.0, v24
	v_rcp_f32_e32 v24, v24
	s_nop 0
	v_fma_f32 v24, v24, -2.0, 1.0
	v_add_f32_e32 v24, 1.0, v24
	v_mul_f32_e32 v16, v16, v24
	v_bfe_u32 v24, v16, 16, 1
	v_add3_u32 v16, v16, v24, s43
	v_or_b32_e32 v24, v22, v101
	v_lshlrev_b32_e32 v168, 1, v24
	v_lshl_add_u64 v[24:25], v[20:21], 0, v[168:169]
	global_store_short_d16_hi v[24:25], v16, off
	ds_read_b32 v16, v121
	s_waitcnt lgkmcnt(0)
	v_fma_f32 v16, v23, v16, v17
	v_mul_f32_e32 v17, 0x3d372713, v16
	v_mul_f32_e32 v17, v16, v17
	v_fma_f32 v17, v16, v17, v16
	v_mul_f32_e32 v17, 0x3f4c422a, v17
	v_add_f32_e32 v17, v17, v17
	v_mul_f32_e32 v17, 0x3fb8aa3b, v17
	v_exp_f32_e32 v17, v17
	v_mul_f32_e32 v16, 0.5, v16
	v_add_f32_e32 v17, 1.0, v17
	v_rcp_f32_e32 v17, v17
	s_nop 0
	v_fma_f32 v17, v17, -2.0, 1.0
	v_add_f32_e32 v17, 1.0, v17
	v_mul_f32_e32 v16, v16, v17
	v_bfe_u32 v17, v16, 16, 1
	v_add3_u32 v24, v16, v17, s43
	v_or_b32_e32 v16, v22, v102
	v_lshlrev_b32_e32 v168, 1, v16
	v_lshl_add_u64 v[16:17], v[20:21], 0, v[168:169]
	global_store_short_d16_hi v[16:17], v24, off
	ds_read_b32 v16, v122
	s_waitcnt lgkmcnt(0)
	v_fma_f32 v16, v23, v16, v18
	v_mul_f32_e32 v17, 0x3d372713, v16
	v_mul_f32_e32 v17, v16, v17
	v_fma_f32 v17, v16, v17, v16
	v_mul_f32_e32 v17, 0x3f4c422a, v17
	v_add_f32_e32 v17, v17, v17
	v_mul_f32_e32 v17, 0x3fb8aa3b, v17
	v_exp_f32_e32 v17, v17
	v_mul_f32_e32 v16, 0.5, v16
	v_add_f32_e32 v17, 1.0, v17
	v_rcp_f32_e32 v17, v17
	s_nop 0
	v_fma_f32 v17, v17, -2.0, 1.0
	v_add_f32_e32 v17, 1.0, v17
	v_mul_f32_e32 v16, v16, v17
	v_bfe_u32 v17, v16, 16, 1
	v_add3_u32 v18, v16, v17, s43
	v_or_b32_e32 v16, v22, v103
	v_lshlrev_b32_e32 v168, 1, v16
	v_lshl_add_u64 v[16:17], v[20:21], 0, v[168:169]
	global_store_short_d16_hi v[16:17], v18, off
	ds_read_b32 v16, v123
	s_waitcnt lgkmcnt(0)
	v_fmac_f32_e32 v19, v23, v16
	v_mul_f32_e32 v16, 0x3d372713, v19
	v_mul_f32_e32 v16, v19, v16
	v_fma_f32 v16, v19, v16, v19
	v_mul_f32_e32 v16, 0x3f4c422a, v16
	v_add_f32_e32 v16, v16, v16
	v_mul_f32_e32 v16, 0x3fb8aa3b, v16
	v_exp_f32_e32 v16, v16
	v_mul_f32_e32 v17, 0.5, v19
	v_add_f32_e32 v16, 1.0, v16
	v_rcp_f32_e32 v16, v16
	s_nop 0
	v_fma_f32 v16, v16, -2.0, 1.0
	v_add_f32_e32 v16, 1.0, v16
	v_mul_f32_e32 v16, v17, v16
	v_bfe_u32 v17, v16, 16, 1
	v_add3_u32 v18, v16, v17, s43
	v_or_b32_e32 v16, v22, v104
	v_lshlrev_b32_e32 v168, 1, v16
	v_lshl_add_u64 v[16:17], v[20:21], 0, v[168:169]
	global_store_short_d16_hi v[16:17], v18, off
	ds_read_b128 v[16:19], v128 offset:4352
	s_waitcnt lgkmcnt(0)
	v_mfma_f32_16x16x32_bf16 v[0:3], v[16:19], v[0:3], 0
	ds_read_b128 v[16:19], v128 offset:4416
	s_waitcnt lgkmcnt(0)
	v_mfma_f32_16x16x32_bf16 v[0:3], v[16:19], v[4:7], v[0:3]
	ds_read_b128 v[4:7], v128 offset:4480
	s_waitcnt lgkmcnt(0)
	v_mfma_f32_16x16x32_bf16 v[0:3], v[4:7], v[8:11], v[0:3]
	ds_read_b128 v[4:7], v128 offset:4544
	s_waitcnt lgkmcnt(0)
	v_mfma_f32_16x16x32_bf16 v[0:3], v[4:7], v[12:15], v[0:3]
	ds_read_b32 v4, v124
	s_waitcnt lgkmcnt(0)
	s_nop 5
	v_fma_f32 v0, v23, v4, v0
	v_mul_f32_e32 v4, 0x3d372713, v0
	v_mul_f32_e32 v4, v0, v4
	v_fma_f32 v4, v0, v4, v0
	v_mul_f32_e32 v4, 0x3f4c422a, v4
	v_add_f32_e32 v4, v4, v4
	v_mul_f32_e32 v4, 0x3fb8aa3b, v4
	v_exp_f32_e32 v4, v4
	v_mul_f32_e32 v0, 0.5, v0
	v_add_f32_e32 v4, 1.0, v4
	v_rcp_f32_e32 v4, v4
	s_nop 0
	v_fma_f32 v4, v4, -2.0, 1.0
	v_add_f32_e32 v4, 1.0, v4
	v_mul_f32_e32 v0, v0, v4
	v_bfe_u32 v4, v0, 16, 1
	v_add3_u32 v0, v0, v4, s43
	v_or_b32_e32 v4, v22, v105
	v_lshlrev_b32_e32 v168, 1, v4
	v_lshl_add_u64 v[4:5], v[20:21], 0, v[168:169]
	global_store_short_d16_hi v[4:5], v0, off
	ds_read_b32 v0, v125
	s_waitcnt lgkmcnt(0)
	v_fma_f32 v0, v23, v0, v1
	v_mul_f32_e32 v1, 0x3d372713, v0
	v_mul_f32_e32 v1, v0, v1
	v_fma_f32 v1, v0, v1, v0
	v_mul_f32_e32 v1, 0x3f4c422a, v1
	v_add_f32_e32 v1, v1, v1
	v_mul_f32_e32 v1, 0x3fb8aa3b, v1
	v_exp_f32_e32 v1, v1
	v_mul_f32_e32 v0, 0.5, v0
	v_add_f32_e32 v1, 1.0, v1
	v_rcp_f32_e32 v1, v1
	s_nop 0
	v_fma_f32 v1, v1, -2.0, 1.0
	v_add_f32_e32 v1, 1.0, v1
	v_mul_f32_e32 v0, v0, v1
	v_bfe_u32 v1, v0, 16, 1
	v_add3_u32 v4, v0, v1, s43
	v_or_b32_e32 v0, v22, v106
	v_lshlrev_b32_e32 v168, 1, v0
	v_lshl_add_u64 v[0:1], v[20:21], 0, v[168:169]
	global_store_short_d16_hi v[0:1], v4, off
	ds_read_b32 v0, v126
	s_waitcnt lgkmcnt(0)
	v_fma_f32 v0, v23, v0, v2
	v_mul_f32_e32 v1, 0x3d372713, v0
	v_mul_f32_e32 v1, v0, v1
	v_fma_f32 v1, v0, v1, v0
	v_mul_f32_e32 v1, 0x3f4c422a, v1
	v_add_f32_e32 v1, v1, v1
	v_mul_f32_e32 v1, 0x3fb8aa3b, v1
	v_exp_f32_e32 v1, v1
	v_mul_f32_e32 v0, 0.5, v0
	v_add_f32_e32 v1, 1.0, v1
	v_rcp_f32_e32 v1, v1
	s_nop 0
	v_fma_f32 v1, v1, -2.0, 1.0
	v_add_f32_e32 v1, 1.0, v1
	v_mul_f32_e32 v0, v0, v1
	v_bfe_u32 v1, v0, 16, 1
	v_add3_u32 v2, v0, v1, s43
	v_or_b32_e32 v0, v22, v107
	v_lshlrev_b32_e32 v168, 1, v0
	v_lshl_add_u64 v[0:1], v[20:21], 0, v[168:169]
	global_store_short_d16_hi v[0:1], v2, off
	ds_read_b32 v0, v127
	s_waitcnt lgkmcnt(0)
	v_fmac_f32_e32 v3, v23, v0
	v_mul_f32_e32 v0, 0x3d372713, v3
	v_mul_f32_e32 v0, v3, v0
	v_fma_f32 v0, v3, v0, v3
	v_mul_f32_e32 v0, 0x3f4c422a, v0
	v_add_f32_e32 v0, v0, v0
	v_mul_f32_e32 v0, 0x3fb8aa3b, v0
	v_exp_f32_e32 v0, v0
	v_mul_f32_e32 v1, 0.5, v3
	v_add_f32_e32 v0, 1.0, v0
	v_rcp_f32_e32 v0, v0
	s_nop 0
	v_fma_f32 v0, v0, -2.0, 1.0
	v_add_f32_e32 v0, 1.0, v0
	v_mul_f32_e32 v0, v1, v0
	v_bfe_u32 v1, v0, 16, 1
	v_add3_u32 v2, v0, v1, s43
	v_or_b32_e32 v0, v22, v108
	v_lshlrev_b32_e32 v168, 1, v0
	v_lshl_add_u64 v[0:1], v[20:21], 0, v[168:169]
	global_store_short_d16_hi v[0:1], v2, off
	s_waitcnt lgkmcnt(0)
	s_andn2_b64 exec, exec, s[22:23]
	s_cbranch_execnz .LBB0_859

.LBB0_892:
	s_mul_i32 s11, s7, 0x6000
	s_add_i32 s11, s11, 0
	v_lshl_add_u32 v11, v7, 2, s11
	v_lshl_add_u32 v12, v4, 2, s11
	ds_read_b128 v[60:63], v11 offset:512
	ds_read_b128 v[64:67], v11 offset:256
	ds_read_b32 v68, v12 offset:1280
	ds_read_b128 v[72:75], v11
	ds_read_b128 v[76:79], v11 offset:768
	ds_read_b128 v[80:83], v11 offset:1024
	ds_read_b128 v[84:87], v11 offset:2048
	ds_read_b128 v[88:91], v11 offset:1792
	ds_read_b32 v92, v12 offset:2816
	ds_read_b128 v[96:99], v11 offset:1536
	ds_read_b128 v[100:103], v11 offset:2304
	ds_read_b128 v[104:107], v11 offset:2560
	s_and_b32 s11, s6, 0x1000
	v_lshl_add_u32 v10, s11, 2, v9
	s_waitcnt lgkmcnt(3)
	ds_read_b128 v[108:111], v11 offset:3584
	ds_read_b128 v[112:115], v11 offset:3328
	ds_read_b32 v116, v12 offset:4352
	ds_read_b128 v[120:123], v11 offset:3072
	ds_read_b128 v[124:127], v11 offset:3840
	ds_read_b128 v[128:131], v11 offset:4096
	v_mul_f32_e32 v30, v5, v68
	v_pk_mul_f32 v[18:19], v[64:65], v[30:31] op_sel_hi:[1,0]
	v_pk_mul_f32 v[20:21], v[66:67], v[30:31] op_sel_hi:[1,0]
	v_pk_mul_f32 v[22:23], v[0:1], v[60:61]
	v_pk_fma_f32 v[22:23], v[2:3], v[62:63], v[22:23]
	v_add_f32_e32 v26, v22, v23
	v_pk_fma_f32 v[14:15], v[0:1], v[72:73], v[18:19]
	v_pk_fma_f32 v[16:17], v[2:3], v[74:75], v[20:21]
	v_add_f32_dpp v26, v26, v26 quad_perm:[1,0,3,2] row_mask:0xf bank_mask:0xf bound_ctrl:1
	s_nop 1
	v_add_f32_dpp v26, v26, v26 quad_perm:[2,3,0,1] row_mask:0xf bank_mask:0xf bound_ctrl:1
	s_nop 1
	v_add_f32_dpp v26, v26, v26 row_half_mirror row_mask:0xf bank_mask:0xf bound_ctrl:1
	s_nop 1
	v_add_f32_dpp v28, v26, v26 row_mirror row_mask:0xf bank_mask:0xf bound_ctrl:1
	v_pk_fma_f32 v[40:41], v[76:77], v[28:29], v[14:15] op_sel_hi:[1,0,1]
	v_pk_fma_f32 v[42:43], v[78:79], v[28:29], v[16:17] op_sel_hi:[1,0,1]
	v_pk_mul_f32 v[22:23], v[14:15], v[84:85]
	v_pk_mul_f32 v[24:25], v[76:77], v[84:85]
	v_pk_fma_f32 v[22:23], v[16:17], v[86:87], v[22:23]
	v_pk_fma_f32 v[24:25], v[78:79], v[86:87], v[24:25]
	v_add_f32_e32 v26, v22, v23
	v_add_f32_e32 v27, v24, v25
	v_fmac_f32_e32 v26, v28, v27
	s_nop 1
	v_add_f32_dpp v26, v26, v26 quad_perm:[1,0,3,2] row_mask:0xf bank_mask:0xf bound_ctrl:1
	v_mul_f32_e32 v30, v5, v92
	v_pk_mul_f32 v[18:19], v[88:89], v[30:31] op_sel_hi:[1,0]
	v_add_f32_dpp v26, v26, v26 quad_perm:[2,3,0,1] row_mask:0xf bank_mask:0xf bound_ctrl:1
	v_pk_mul_f32 v[20:21], v[90:91], v[30:31] op_sel_hi:[1,0]
	s_nop 0
	v_add_f32_dpp v26, v26, v26 row_half_mirror row_mask:0xf bank_mask:0xf bound_ctrl:1
	s_nop 1
	v_add_f32_dpp v28, v26, v26 row_mirror row_mask:0xf bank_mask:0xf bound_ctrl:1
	s_waitcnt lgkmcnt(3)
	ds_read_b128 v[132:135], v11 offset:5120
	ds_read_b128 v[136:139], v11 offset:4864
	ds_read_b32 v140, v12 offset:5888
	ds_read_b128 v[144:147], v11 offset:4608
	ds_read_b128 v[148:151], v11 offset:5376
	ds_read_b128 v[152:155], v11 offset:5632
	v_pk_fma_f32 v[14:15], v[40:41], v[96:97], v[18:19]
	v_pk_fma_f32 v[16:17], v[42:43], v[98:99], v[20:21]
	v_pk_fma_f32 v[0:1], v[100:101], v[28:29], v[14:15] op_sel_hi:[1,0,1]
	v_pk_fma_f32 v[2:3], v[102:103], v[28:29], v[16:17] op_sel_hi:[1,0,1]
	v_pk_mul_f32 v[22:23], v[14:15], v[108:109]
	v_pk_mul_f32 v[24:25], v[100:101], v[108:109]
	v_pk_fma_f32 v[22:23], v[16:17], v[110:111], v[22:23]
	v_pk_fma_f32 v[24:25], v[102:103], v[110:111], v[24:25]
	v_add_f32_e32 v26, v22, v23
	v_add_f32_e32 v27, v24, v25
	v_fmac_f32_e32 v26, v28, v27
	s_nop 1
	v_add_f32_dpp v26, v26, v26 quad_perm:[1,0,3,2] row_mask:0xf bank_mask:0xf bound_ctrl:1
	v_pk_mul_f32 v[32:33], v[40:41], v[80:81]
	v_pk_fma_f32 v[32:33], v[42:43], v[82:83], v[32:33]
	v_add_f32_dpp v26, v26, v26 quad_perm:[2,3,0,1] row_mask:0xf bank_mask:0xf bound_ctrl:1
	v_add_f32_e32 v32, v32, v33
	ds_write_b32 v10, v32
	v_add_f32_dpp v26, v26, v26 row_half_mirror row_mask:0xf bank_mask:0xf bound_ctrl:1
	v_mul_f32_e32 v30, v5, v116
	v_pk_mul_f32 v[18:19], v[112:113], v[30:31] op_sel_hi:[1,0]
	v_add_f32_dpp v28, v26, v26 row_mirror row_mask:0xf bank_mask:0xf bound_ctrl:1
	v_pk_mul_f32 v[20:21], v[114:115], v[30:31] op_sel_hi:[1,0]
	s_waitcnt lgkmcnt(4)
	ds_read_b128 v[60:63], v11 offset:6656
	ds_read_b128 v[64:67], v11 offset:6400
	ds_read_b32 v68, v12 offset:7424
	ds_read_b128 v[72:75], v11 offset:6144
	ds_read_b128 v[76:79], v11 offset:6912
	ds_read_b128 v[80:83], v11 offset:7168
	v_pk_fma_f32 v[14:15], v[0:1], v[120:121], v[18:19]
	v_pk_fma_f32 v[16:17], v[2:3], v[122:123], v[20:21]
	v_pk_fma_f32 v[40:41], v[124:125], v[28:29], v[14:15] op_sel_hi:[1,0,1]
	v_pk_fma_f32 v[42:43], v[126:127], v[28:29], v[16:17] op_sel_hi:[1,0,1]
	v_pk_mul_f32 v[22:23], v[14:15], v[132:133]
	v_pk_mul_f32 v[24:25], v[124:125], v[132:133]
	v_pk_fma_f32 v[22:23], v[16:17], v[134:135], v[22:23]
	v_pk_fma_f32 v[24:25], v[126:127], v[134:135], v[24:25]
	v_add_f32_e32 v26, v22, v23
	v_add_f32_e32 v27, v24, v25
	v_fmac_f32_e32 v26, v28, v27
	s_nop 1
	v_add_f32_dpp v26, v26, v26 quad_perm:[1,0,3,2] row_mask:0xf bank_mask:0xf bound_ctrl:1
	v_pk_mul_f32 v[32:33], v[0:1], v[104:105]
	v_pk_fma_f32 v[32:33], v[2:3], v[106:107], v[32:33]
	v_add_f32_dpp v26, v26, v26 quad_perm:[2,3,0,1] row_mask:0xf bank_mask:0xf bound_ctrl:1
	v_add_f32_e32 v32, v32, v33
	ds_write_b32 v10, v32 offset:1024
	v_add_f32_dpp v26, v26, v26 row_half_mirror row_mask:0xf bank_mask:0xf bound_ctrl:1
	v_mul_f32_e32 v30, v5, v140
	v_pk_mul_f32 v[18:19], v[136:137], v[30:31] op_sel_hi:[1,0]
	v_add_f32_dpp v28, v26, v26 row_mirror row_mask:0xf bank_mask:0xf bound_ctrl:1
	v_pk_mul_f32 v[20:21], v[138:139], v[30:31] op_sel_hi:[1,0]
	s_waitcnt lgkmcnt(4)
	ds_read_b128 v[84:87], v11 offset:8192
	ds_read_b128 v[88:91], v11 offset:7936
	ds_read_b32 v92, v12 offset:8960
	ds_read_b128 v[96:99], v11 offset:7680
	ds_read_b128 v[100:103], v11 offset:8448
	ds_read_b128 v[104:107], v11 offset:8704
	v_pk_fma_f32 v[14:15], v[40:41], v[144:145], v[18:19]
	v_pk_fma_f32 v[16:17], v[42:43], v[146:147], v[20:21]
	v_pk_fma_f32 v[0:1], v[148:149], v[28:29], v[14:15] op_sel_hi:[1,0,1]
	v_pk_fma_f32 v[2:3], v[150:151], v[28:29], v[16:17] op_sel_hi:[1,0,1]
	v_pk_mul_f32 v[22:23], v[14:15], v[60:61]
	v_pk_mul_f32 v[24:25], v[148:149], v[60:61]
	v_pk_fma_f32 v[22:23], v[16:17], v[62:63], v[22:23]
	v_pk_fma_f32 v[24:25], v[150:151], v[62:63], v[24:25]
	v_add_f32_e32 v26, v22, v23
	v_add_f32_e32 v27, v24, v25
	v_fmac_f32_e32 v26, v28, v27
	s_nop 1
	v_add_f32_dpp v26, v26, v26 quad_perm:[1,0,3,2] row_mask:0xf bank_mask:0xf bound_ctrl:1
	v_pk_mul_f32 v[32:33], v[40:41], v[128:129]
	v_pk_fma_f32 v[32:33], v[42:43], v[130:131], v[32:33]
	v_add_f32_dpp v26, v26, v26 quad_perm:[2,3,0,1] row_mask:0xf bank_mask:0xf bound_ctrl:1
	v_add_f32_e32 v32, v32, v33
	ds_write_b32 v10, v32 offset:2048
	v_add_f32_dpp v26, v26, v26 row_half_mirror row_mask:0xf bank_mask:0xf bound_ctrl:1
	v_mul_f32_e32 v30, v5, v68
	v_pk_mul_f32 v[18:19], v[64:65], v[30:31] op_sel_hi:[1,0]
	v_add_f32_dpp v28, v26, v26 row_mirror row_mask:0xf bank_mask:0xf bound_ctrl:1
	v_pk_mul_f32 v[20:21], v[66:67], v[30:31] op_sel_hi:[1,0]
	s_waitcnt lgkmcnt(4)
	ds_read_b128 v[108:111], v11 offset:9728
	ds_read_b128 v[112:115], v11 offset:9472
	ds_read_b32 v116, v12 offset:10496
	ds_read_b128 v[120:123], v11 offset:9216
	ds_read_b128 v[124:127], v11 offset:9984
	ds_read_b128 v[128:131], v11 offset:10240
	v_pk_fma_f32 v[14:15], v[0:1], v[72:73], v[18:19]
	v_pk_fma_f32 v[16:17], v[2:3], v[74:75], v[20:21]
	v_pk_fma_f32 v[40:41], v[76:77], v[28:29], v[14:15] op_sel_hi:[1,0,1]
	v_pk_fma_f32 v[42:43], v[78:79], v[28:29], v[16:17] op_sel_hi:[1,0,1]
	v_pk_mul_f32 v[22:23], v[14:15], v[84:85]
	v_pk_mul_f32 v[24:25], v[76:77], v[84:85]
	v_pk_fma_f32 v[22:23], v[16:17], v[86:87], v[22:23]
	v_pk_fma_f32 v[24:25], v[78:79], v[86:87], v[24:25]
	v_add_f32_e32 v26, v22, v23
	v_add_f32_e32 v27, v24, v25
	v_fmac_f32_e32 v26, v28, v27
	s_nop 1
	v_add_f32_dpp v26, v26, v26 quad_perm:[1,0,3,2] row_mask:0xf bank_mask:0xf bound_ctrl:1
	v_pk_mul_f32 v[32:33], v[0:1], v[152:153]
	v_pk_fma_f32 v[32:33], v[2:3], v[154:155], v[32:33]
	v_add_f32_dpp v26, v26, v26 quad_perm:[2,3,0,1] row_mask:0xf bank_mask:0xf bound_ctrl:1
	v_add_f32_e32 v32, v32, v33
	ds_write_b32 v10, v32 offset:3072
	v_add_f32_dpp v26, v26, v26 row_half_mirror row_mask:0xf bank_mask:0xf bound_ctrl:1
	v_mul_f32_e32 v30, v5, v92
	v_pk_mul_f32 v[18:19], v[88:89], v[30:31] op_sel_hi:[1,0]
	v_add_f32_dpp v28, v26, v26 row_mirror row_mask:0xf bank_mask:0xf bound_ctrl:1
	v_pk_mul_f32 v[20:21], v[90:91], v[30:31] op_sel_hi:[1,0]
	s_waitcnt lgkmcnt(4)
	ds_read_b128 v[132:135], v11 offset:11264
	ds_read_b128 v[136:139], v11 offset:11008
	ds_read_b32 v140, v12 offset:12032
	ds_read_b128 v[144:147], v11 offset:10752
	ds_read_b128 v[148:151], v11 offset:11520
	ds_read_b128 v[152:155], v11 offset:11776
	v_pk_fma_f32 v[14:15], v[40:41], v[96:97], v[18:19]
	v_pk_fma_f32 v[16:17], v[42:43], v[98:99], v[20:21]
	v_pk_fma_f32 v[0:1], v[100:101], v[28:29], v[14:15] op_sel_hi:[1,0,1]
	v_pk_fma_f32 v[2:3], v[102:103], v[28:29], v[16:17] op_sel_hi:[1,0,1]
	v_pk_mul_f32 v[22:23], v[14:15], v[108:109]
	v_pk_mul_f32 v[24:25], v[100:101], v[108:109]
	v_pk_fma_f32 v[22:23], v[16:17], v[110:111], v[22:23]
	v_pk_fma_f32 v[24:25], v[102:103], v[110:111], v[24:25]
	v_add_f32_e32 v26, v22, v23
	v_add_f32_e32 v27, v24, v25
	v_fmac_f32_e32 v26, v28, v27
	s_nop 1
	v_add_f32_dpp v26, v26, v26 quad_perm:[1,0,3,2] row_mask:0xf bank_mask:0xf bound_ctrl:1
	v_pk_mul_f32 v[32:33], v[40:41], v[80:81]
	v_pk_fma_f32 v[32:33], v[42:43], v[82:83], v[32:33]
	v_add_f32_dpp v26, v26, v26 quad_perm:[2,3,0,1] row_mask:0xf bank_mask:0xf bound_ctrl:1
	v_add_f32_e32 v32, v32, v33
	ds_write_b32 v10, v32 offset:4096
	v_add_f32_dpp v26, v26, v26 row_half_mirror row_mask:0xf bank_mask:0xf bound_ctrl:1
	v_mul_f32_e32 v30, v5, v116
	v_pk_mul_f32 v[18:19], v[112:113], v[30:31] op_sel_hi:[1,0]
	v_add_f32_dpp v28, v26, v26 row_mirror row_mask:0xf bank_mask:0xf bound_ctrl:1
	v_pk_mul_f32 v[20:21], v[114:115], v[30:31] op_sel_hi:[1,0]
	s_waitcnt lgkmcnt(4)
	ds_read_b128 v[60:63], v11 offset:12800
	ds_read_b128 v[64:67], v11 offset:12544
	ds_read_b32 v68, v12 offset:13568
	ds_read_b128 v[72:75], v11 offset:12288
	ds_read_b128 v[76:79], v11 offset:13056
	ds_read_b128 v[80:83], v11 offset:13312
	v_pk_fma_f32 v[14:15], v[0:1], v[120:121], v[18:19]
	v_pk_fma_f32 v[16:17], v[2:3], v[122:123], v[20:21]
	v_pk_fma_f32 v[40:41], v[124:125], v[28:29], v[14:15] op_sel_hi:[1,0,1]
	v_pk_fma_f32 v[42:43], v[126:127], v[28:29], v[16:17] op_sel_hi:[1,0,1]
	v_pk_mul_f32 v[22:23], v[14:15], v[132:133]
	v_pk_mul_f32 v[24:25], v[124:125], v[132:133]
	v_pk_fma_f32 v[22:23], v[16:17], v[134:135], v[22:23]
	v_pk_fma_f32 v[24:25], v[126:127], v[134:135], v[24:25]
	v_add_f32_e32 v26, v22, v23
	v_add_f32_e32 v27, v24, v25
	v_fmac_f32_e32 v26, v28, v27
	s_nop 1
	v_add_f32_dpp v26, v26, v26 quad_perm:[1,0,3,2] row_mask:0xf bank_mask:0xf bound_ctrl:1
	v_pk_mul_f32 v[32:33], v[0:1], v[104:105]
	v_pk_fma_f32 v[32:33], v[2:3], v[106:107], v[32:33]
	v_add_f32_dpp v26, v26, v26 quad_perm:[2,3,0,1] row_mask:0xf bank_mask:0xf bound_ctrl:1
	v_add_f32_e32 v32, v32, v33
	ds_write_b32 v10, v32 offset:5120
	v_add_f32_dpp v26, v26, v26 row_half_mirror row_mask:0xf bank_mask:0xf bound_ctrl:1
	v_mul_f32_e32 v30, v5, v140
	v_pk_mul_f32 v[18:19], v[136:137], v[30:31] op_sel_hi:[1,0]
	v_add_f32_dpp v28, v26, v26 row_mirror row_mask:0xf bank_mask:0xf bound_ctrl:1
	v_pk_mul_f32 v[20:21], v[138:139], v[30:31] op_sel_hi:[1,0]
	s_waitcnt lgkmcnt(4)
	ds_read_b128 v[84:87], v11 offset:14336
	ds_read_b128 v[88:91], v11 offset:14080
	ds_read_b32 v92, v12 offset:15104
	ds_read_b128 v[96:99], v11 offset:13824
	ds_read_b128 v[100:103], v11 offset:14592
	ds_read_b128 v[104:107], v11 offset:14848
	v_pk_fma_f32 v[14:15], v[40:41], v[144:145], v[18:19]
	v_pk_fma_f32 v[16:17], v[42:43], v[146:147], v[20:21]
	v_pk_fma_f32 v[0:1], v[148:149], v[28:29], v[14:15] op_sel_hi:[1,0,1]
	v_pk_fma_f32 v[2:3], v[150:151], v[28:29], v[16:17] op_sel_hi:[1,0,1]
	v_pk_mul_f32 v[22:23], v[14:15], v[60:61]
	v_pk_mul_f32 v[24:25], v[148:149], v[60:61]
	v_pk_fma_f32 v[22:23], v[16:17], v[62:63], v[22:23]
	v_pk_fma_f32 v[24:25], v[150:151], v[62:63], v[24:25]
	v_add_f32_e32 v26, v22, v23
	v_add_f32_e32 v27, v24, v25
	v_fmac_f32_e32 v26, v28, v27
	s_nop 1
	v_add_f32_dpp v26, v26, v26 quad_perm:[1,0,3,2] row_mask:0xf bank_mask:0xf bound_ctrl:1
	v_pk_mul_f32 v[32:33], v[40:41], v[128:129]
	v_pk_fma_f32 v[32:33], v[42:43], v[130:131], v[32:33]
	v_add_f32_dpp v26, v26, v26 quad_perm:[2,3,0,1] row_mask:0xf bank_mask:0xf bound_ctrl:1
	v_add_f32_e32 v32, v32, v33
	ds_write_b32 v10, v32 offset:6144
	v_add_f32_dpp v26, v26, v26 row_half_mirror row_mask:0xf bank_mask:0xf bound_ctrl:1
	v_mul_f32_e32 v30, v5, v68
	v_pk_mul_f32 v[18:19], v[64:65], v[30:31] op_sel_hi:[1,0]
	v_add_f32_dpp v28, v26, v26 row_mirror row_mask:0xf bank_mask:0xf bound_ctrl:1
	v_pk_mul_f32 v[20:21], v[66:67], v[30:31] op_sel_hi:[1,0]
	s_waitcnt lgkmcnt(4)
	ds_read_b128 v[108:111], v11 offset:15872
	ds_read_b128 v[112:115], v11 offset:15616
	ds_read_b32 v116, v12 offset:16640
	ds_read_b128 v[120:123], v11 offset:15360
	ds_read_b128 v[124:127], v11 offset:16128
	ds_read_b128 v[128:131], v11 offset:16384
	v_pk_fma_f32 v[14:15], v[0:1], v[72:73], v[18:19]
	v_pk_fma_f32 v[16:17], v[2:3], v[74:75], v[20:21]
	v_pk_fma_f32 v[40:41], v[76:77], v[28:29], v[14:15] op_sel_hi:[1,0,1]
	v_pk_fma_f32 v[42:43], v[78:79], v[28:29], v[16:17] op_sel_hi:[1,0,1]
	v_pk_mul_f32 v[22:23], v[14:15], v[84:85]
	v_pk_mul_f32 v[24:25], v[76:77], v[84:85]
	v_pk_fma_f32 v[22:23], v[16:17], v[86:87], v[22:23]
	v_pk_fma_f32 v[24:25], v[78:79], v[86:87], v[24:25]
	v_add_f32_e32 v26, v22, v23
	v_add_f32_e32 v27, v24, v25
	v_fmac_f32_e32 v26, v28, v27
	s_nop 1
	v_add_f32_dpp v26, v26, v26 quad_perm:[1,0,3,2] row_mask:0xf bank_mask:0xf bound_ctrl:1
	v_pk_mul_f32 v[32:33], v[0:1], v[152:153]
	v_pk_fma_f32 v[32:33], v[2:3], v[154:155], v[32:33]
	v_add_f32_dpp v26, v26, v26 quad_perm:[2,3,0,1] row_mask:0xf bank_mask:0xf bound_ctrl:1
	v_add_f32_e32 v32, v32, v33
	ds_write_b32 v10, v32 offset:7168
	v_add_f32_dpp v26, v26, v26 row_half_mirror row_mask:0xf bank_mask:0xf bound_ctrl:1
	v_mul_f32_e32 v30, v5, v92
	v_pk_mul_f32 v[18:19], v[88:89], v[30:31] op_sel_hi:[1,0]
	v_add_f32_dpp v28, v26, v26 row_mirror row_mask:0xf bank_mask:0xf bound_ctrl:1
	v_pk_mul_f32 v[20:21], v[90:91], v[30:31] op_sel_hi:[1,0]
	s_waitcnt lgkmcnt(4)
	ds_read_b128 v[132:135], v11 offset:17408
	ds_read_b128 v[136:139], v11 offset:17152
	ds_read_b32 v140, v12 offset:18176
	ds_read_b128 v[144:147], v11 offset:16896
	ds_read_b128 v[148:151], v11 offset:17664
	ds_read_b128 v[152:155], v11 offset:17920
	v_pk_fma_f32 v[14:15], v[40:41], v[96:97], v[18:19]
	v_pk_fma_f32 v[16:17], v[42:43], v[98:99], v[20:21]
	v_pk_fma_f32 v[0:1], v[100:101], v[28:29], v[14:15] op_sel_hi:[1,0,1]
	v_pk_fma_f32 v[2:3], v[102:103], v[28:29], v[16:17] op_sel_hi:[1,0,1]
	v_pk_mul_f32 v[22:23], v[14:15], v[108:109]
	v_pk_mul_f32 v[24:25], v[100:101], v[108:109]
	v_pk_fma_f32 v[22:23], v[16:17], v[110:111], v[22:23]
	v_pk_fma_f32 v[24:25], v[102:103], v[110:111], v[24:25]
	v_add_f32_e32 v26, v22, v23
	v_add_f32_e32 v27, v24, v25
	v_fmac_f32_e32 v26, v28, v27
	s_nop 1
	v_add_f32_dpp v26, v26, v26 quad_perm:[1,0,3,2] row_mask:0xf bank_mask:0xf bound_ctrl:1
	v_pk_mul_f32 v[32:33], v[40:41], v[80:81]
	v_pk_fma_f32 v[32:33], v[42:43], v[82:83], v[32:33]
	v_add_f32_dpp v26, v26, v26 quad_perm:[2,3,0,1] row_mask:0xf bank_mask:0xf bound_ctrl:1
	v_add_f32_e32 v32, v32, v33
	ds_write_b32 v10, v32 offset:8192
	v_add_f32_dpp v26, v26, v26 row_half_mirror row_mask:0xf bank_mask:0xf bound_ctrl:1
	v_mul_f32_e32 v30, v5, v116
	v_pk_mul_f32 v[18:19], v[112:113], v[30:31] op_sel_hi:[1,0]
	v_add_f32_dpp v28, v26, v26 row_mirror row_mask:0xf bank_mask:0xf bound_ctrl:1
	v_pk_mul_f32 v[20:21], v[114:115], v[30:31] op_sel_hi:[1,0]
	s_waitcnt lgkmcnt(4)
	ds_read_b128 v[60:63], v11 offset:18944
	ds_read_b128 v[64:67], v11 offset:18688
	ds_read_b32 v68, v12 offset:19712
	ds_read_b128 v[72:75], v11 offset:18432
	ds_read_b128 v[76:79], v11 offset:19200
	ds_read_b128 v[80:83], v11 offset:19456
	v_pk_fma_f32 v[14:15], v[0:1], v[120:121], v[18:19]
	v_pk_fma_f32 v[16:17], v[2:3], v[122:123], v[20:21]
	v_pk_fma_f32 v[40:41], v[124:125], v[28:29], v[14:15] op_sel_hi:[1,0,1]
	v_pk_fma_f32 v[42:43], v[126:127], v[28:29], v[16:17] op_sel_hi:[1,0,1]
	v_pk_mul_f32 v[22:23], v[14:15], v[132:133]
	v_pk_mul_f32 v[24:25], v[124:125], v[132:133]
	v_pk_fma_f32 v[22:23], v[16:17], v[134:135], v[22:23]
	v_pk_fma_f32 v[24:25], v[126:127], v[134:135], v[24:25]
	v_add_f32_e32 v26, v22, v23
	v_add_f32_e32 v27, v24, v25
	v_fmac_f32_e32 v26, v28, v27
	s_nop 1
	v_add_f32_dpp v26, v26, v26 quad_perm:[1,0,3,2] row_mask:0xf bank_mask:0xf bound_ctrl:1
	v_pk_mul_f32 v[32:33], v[0:1], v[104:105]
	v_pk_fma_f32 v[32:33], v[2:3], v[106:107], v[32:33]
	v_add_f32_dpp v26, v26, v26 quad_perm:[2,3,0,1] row_mask:0xf bank_mask:0xf bound_ctrl:1
	v_add_f32_e32 v32, v32, v33
	ds_write_b32 v10, v32 offset:9216
	v_add_f32_dpp v26, v26, v26 row_half_mirror row_mask:0xf bank_mask:0xf bound_ctrl:1
	v_mul_f32_e32 v30, v5, v140
	v_pk_mul_f32 v[18:19], v[136:137], v[30:31] op_sel_hi:[1,0]
	v_add_f32_dpp v28, v26, v26 row_mirror row_mask:0xf bank_mask:0xf bound_ctrl:1
	v_pk_mul_f32 v[20:21], v[138:139], v[30:31] op_sel_hi:[1,0]
	s_waitcnt lgkmcnt(4)
	ds_read_b128 v[84:87], v11 offset:20480
	ds_read_b128 v[88:91], v11 offset:20224
	ds_read_b32 v92, v12 offset:21248
	ds_read_b128 v[96:99], v11 offset:19968
	ds_read_b128 v[100:103], v11 offset:20736
	ds_read_b128 v[104:107], v11 offset:20992
	v_pk_fma_f32 v[14:15], v[40:41], v[144:145], v[18:19]
	v_pk_fma_f32 v[16:17], v[42:43], v[146:147], v[20:21]
	v_pk_fma_f32 v[0:1], v[148:149], v[28:29], v[14:15] op_sel_hi:[1,0,1]
	v_pk_fma_f32 v[2:3], v[150:151], v[28:29], v[16:17] op_sel_hi:[1,0,1]
	v_pk_mul_f32 v[22:23], v[14:15], v[60:61]
	v_pk_mul_f32 v[24:25], v[148:149], v[60:61]
	v_pk_fma_f32 v[22:23], v[16:17], v[62:63], v[22:23]
	v_pk_fma_f32 v[24:25], v[150:151], v[62:63], v[24:25]
	v_add_f32_e32 v26, v22, v23
	v_add_f32_e32 v27, v24, v25
	v_fmac_f32_e32 v26, v28, v27
	s_nop 1
	v_add_f32_dpp v26, v26, v26 quad_perm:[1,0,3,2] row_mask:0xf bank_mask:0xf bound_ctrl:1
	v_pk_mul_f32 v[32:33], v[40:41], v[128:129]
	v_pk_fma_f32 v[32:33], v[42:43], v[130:131], v[32:33]
	v_add_f32_dpp v26, v26, v26 quad_perm:[2,3,0,1] row_mask:0xf bank_mask:0xf bound_ctrl:1
	v_add_f32_e32 v32, v32, v33
	ds_write_b32 v10, v32 offset:10240
	v_add_f32_dpp v26, v26, v26 row_half_mirror row_mask:0xf bank_mask:0xf bound_ctrl:1
	v_mul_f32_e32 v30, v5, v68
	v_pk_mul_f32 v[18:19], v[64:65], v[30:31] op_sel_hi:[1,0]
	v_add_f32_dpp v28, v26, v26 row_mirror row_mask:0xf bank_mask:0xf bound_ctrl:1
	v_pk_mul_f32 v[20:21], v[66:67], v[30:31] op_sel_hi:[1,0]
	s_waitcnt lgkmcnt(4)
	ds_read_b128 v[108:111], v11 offset:22016
	ds_read_b128 v[112:115], v11 offset:21760
	ds_read_b32 v116, v12 offset:22784
	ds_read_b128 v[120:123], v11 offset:21504
	ds_read_b128 v[124:127], v11 offset:22272
	ds_read_b128 v[128:131], v11 offset:22528
	v_pk_fma_f32 v[14:15], v[0:1], v[72:73], v[18:19]
	v_pk_fma_f32 v[16:17], v[2:3], v[74:75], v[20:21]
	v_pk_fma_f32 v[40:41], v[76:77], v[28:29], v[14:15] op_sel_hi:[1,0,1]
	v_pk_fma_f32 v[42:43], v[78:79], v[28:29], v[16:17] op_sel_hi:[1,0,1]
	v_pk_mul_f32 v[22:23], v[14:15], v[84:85]
	v_pk_mul_f32 v[24:25], v[76:77], v[84:85]
	v_pk_fma_f32 v[22:23], v[16:17], v[86:87], v[22:23]
	v_pk_fma_f32 v[24:25], v[78:79], v[86:87], v[24:25]
	v_add_f32_e32 v26, v22, v23
	v_add_f32_e32 v27, v24, v25
	v_fmac_f32_e32 v26, v28, v27
	s_nop 1
	v_add_f32_dpp v26, v26, v26 quad_perm:[1,0,3,2] row_mask:0xf bank_mask:0xf bound_ctrl:1
	v_pk_mul_f32 v[32:33], v[0:1], v[152:153]
	v_pk_fma_f32 v[32:33], v[2:3], v[154:155], v[32:33]
	v_add_f32_dpp v26, v26, v26 quad_perm:[2,3,0,1] row_mask:0xf bank_mask:0xf bound_ctrl:1
	v_add_f32_e32 v32, v32, v33
	ds_write_b32 v10, v32 offset:11264
	v_add_f32_dpp v26, v26, v26 row_half_mirror row_mask:0xf bank_mask:0xf bound_ctrl:1
	v_mul_f32_e32 v30, v5, v92
	v_pk_mul_f32 v[18:19], v[88:89], v[30:31] op_sel_hi:[1,0]
	v_add_f32_dpp v28, v26, v26 row_mirror row_mask:0xf bank_mask:0xf bound_ctrl:1
	v_pk_mul_f32 v[20:21], v[90:91], v[30:31] op_sel_hi:[1,0]
	s_waitcnt lgkmcnt(4)
	ds_read_b128 v[132:135], v11 offset:23552
	ds_read_b128 v[136:139], v11 offset:23296
	ds_read_b32 v140, v12 offset:24320
	ds_read_b128 v[144:147], v11 offset:23040
	ds_read_b128 v[148:151], v11 offset:23808
	ds_read_b128 v[152:155], v11 offset:24064
	v_pk_fma_f32 v[14:15], v[40:41], v[96:97], v[18:19]
	v_pk_fma_f32 v[16:17], v[42:43], v[98:99], v[20:21]
	v_pk_fma_f32 v[0:1], v[100:101], v[28:29], v[14:15] op_sel_hi:[1,0,1]
	v_pk_fma_f32 v[2:3], v[102:103], v[28:29], v[16:17] op_sel_hi:[1,0,1]
	v_pk_mul_f32 v[22:23], v[14:15], v[108:109]
	v_pk_mul_f32 v[24:25], v[100:101], v[108:109]
	v_pk_fma_f32 v[22:23], v[16:17], v[110:111], v[22:23]
	v_pk_fma_f32 v[24:25], v[102:103], v[110:111], v[24:25]
	v_add_f32_e32 v26, v22, v23
	v_add_f32_e32 v27, v24, v25
	v_fmac_f32_e32 v26, v28, v27
	s_nop 1
	v_add_f32_dpp v26, v26, v26 quad_perm:[1,0,3,2] row_mask:0xf bank_mask:0xf bound_ctrl:1
	v_pk_mul_f32 v[32:33], v[40:41], v[80:81]
	v_pk_fma_f32 v[32:33], v[42:43], v[82:83], v[32:33]
	v_add_f32_dpp v26, v26, v26 quad_perm:[2,3,0,1] row_mask:0xf bank_mask:0xf bound_ctrl:1
	v_add_f32_e32 v32, v32, v33
	ds_write_b32 v10, v32 offset:12288
	v_add_f32_dpp v26, v26, v26 row_half_mirror row_mask:0xf bank_mask:0xf bound_ctrl:1
	v_mul_f32_e32 v30, v5, v116
	v_pk_mul_f32 v[18:19], v[112:113], v[30:31] op_sel_hi:[1,0]
	v_add_f32_dpp v28, v26, v26 row_mirror row_mask:0xf bank_mask:0xf bound_ctrl:1
	v_pk_mul_f32 v[20:21], v[114:115], v[30:31] op_sel_hi:[1,0]
	s_waitcnt lgkmcnt(4)
	v_pk_fma_f32 v[14:15], v[0:1], v[120:121], v[18:19]
	v_pk_fma_f32 v[16:17], v[2:3], v[122:123], v[20:21]
	v_pk_fma_f32 v[40:41], v[124:125], v[28:29], v[14:15] op_sel_hi:[1,0,1]
	v_pk_fma_f32 v[42:43], v[126:127], v[28:29], v[16:17] op_sel_hi:[1,0,1]
	v_pk_mul_f32 v[22:23], v[14:15], v[132:133]
	v_pk_mul_f32 v[24:25], v[124:125], v[132:133]
	v_pk_fma_f32 v[22:23], v[16:17], v[134:135], v[22:23]
	v_pk_fma_f32 v[24:25], v[126:127], v[134:135], v[24:25]
	v_add_f32_e32 v26, v22, v23
	v_add_f32_e32 v27, v24, v25
	v_fmac_f32_e32 v26, v28, v27
	s_nop 1
	v_add_f32_dpp v26, v26, v26 quad_perm:[1,0,3,2] row_mask:0xf bank_mask:0xf bound_ctrl:1
	v_pk_mul_f32 v[32:33], v[0:1], v[104:105]
	v_pk_fma_f32 v[32:33], v[2:3], v[106:107], v[32:33]
	v_add_f32_dpp v26, v26, v26 quad_perm:[2,3,0,1] row_mask:0xf bank_mask:0xf bound_ctrl:1
	v_add_f32_e32 v32, v32, v33
	ds_write_b32 v10, v32 offset:13312
	v_add_f32_dpp v26, v26, v26 row_half_mirror row_mask:0xf bank_mask:0xf bound_ctrl:1
	v_mul_f32_e32 v30, v5, v140
	v_pk_mul_f32 v[18:19], v[136:137], v[30:31] op_sel_hi:[1,0]
	v_add_f32_dpp v28, v26, v26 row_mirror row_mask:0xf bank_mask:0xf bound_ctrl:1
	v_pk_mul_f32 v[20:21], v[138:139], v[30:31] op_sel_hi:[1,0]
	s_waitcnt lgkmcnt(0)
	v_pk_fma_f32 v[14:15], v[40:41], v[144:145], v[18:19]
	v_pk_fma_f32 v[16:17], v[42:43], v[146:147], v[20:21]
	v_pk_fma_f32 v[0:1], v[148:149], v[28:29], v[14:15] op_sel_hi:[1,0,1]
	v_pk_fma_f32 v[2:3], v[150:151], v[28:29], v[16:17] op_sel_hi:[1,0,1]
	v_pk_mul_f32 v[32:33], v[40:41], v[128:129]
	v_pk_fma_f32 v[32:33], v[42:43], v[130:131], v[32:33]
	v_add_f32_e32 v32, v32, v33
	ds_write_b32 v10, v32 offset:14336
	v_mul_f32_e32 v33, v155, v3
	v_fmac_f32_e32 v33, v2, v154
	v_fmac_f32_e32 v33, v1, v153
	v_fmac_f32_e32 v33, v0, v152
	ds_write_b32 v10, v33 offset:15360
	s_add_i32 s11, s7, 1
	s_cmp_lg_u32 s7, 3
	s_cselect_b32 s7, s11, 0
	s_waitcnt lgkmcnt(0)
	s_addk_i32 s6, 0x1000
	s_cmp_eq_u32 s6, 0x80000
	s_barrier
	s_cbranch_scc0 .LBB0_892
	s_load_dwordx2 s[6:7], s[0:1], 0x150
	s_and_b64 s[12:13], s[4:5], exec
	s_mov_b32 s11, 0x2ee01800
	s_cselect_b32 s11, s11, 0x2ed81800
	v_ashrrev_i32_e32 v5, 31, v4
	s_waitcnt lgkmcnt(0)
	s_add_u32 s11, s6, s11
	s_addc_u32 s12, s7, 0
	s_lshl_b32 s6, s9, 2
	s_add_i32 s6, s6, s10
	s_ashr_i32 s7, s6, 31
	s_lshl_b64 s[6:7], s[6:7], 14
	s_add_u32 s6, s11, s6
	s_addc_u32 s7, s12, s7
	v_lshlrev_b64 v[4:5], 8, v[4:5]
	v_lshl_add_u64 v[4:5], s[6:7], 0, v[4:5]
	v_lshlrev_b32_e32 v168, 2, v7
	v_lshl_add_u64 v[4:5], v[4:5], 0, v[168:169]
	s_mov_b64 s[6:7], 0
	global_store_dwordx4 v[4:5], v[0:3], off
